# RG-LRU half-panel loop hand-written (tile loop, permlane gathers instead of bpermute chains), both instances
# speedup vs baseline: 1.0356x; 1.0004x over previous
.LBB0_1052:
	s_and_b64 vcc, exec, s[42:43]
	s_cbranch_vccz .Llru_c_bwd
	s_mov_b32 s49, 0
	s_mov_b32 s12, 0x1100
	s_mov_b32 s100, 0x10000
	s_mov_b32 s101, 0
.Llru_cf_half:
	s_xor_b32 s4, s49, s24
	s_lshl_b32 s4, s4, 7
	s_add_i32 s13, s4, s19
	v_add_u32_e32 v134, s13, v157
	v_mad_u32_u24 v36, v134, s30, v174
	v_add_u32_e32 v134, s13, v175
	v_mad_u32_u24 v37, v134, s30, v156
	s_add_i32 s20, s3, s13
	v_add_u32_e32 v134, s20, v175
	v_add_u32_e32 v134, 1, v134
	v_ashrrev_i32_e32 v135, 31, v134
	v_lshlrev_b64 v[134:135], 12, v[134:135]
	v_lshl_add_u64 v[38:39], v[118:119], 0, v[134:135]
	s_mov_b32 s20, 0x2000
	s_mov_b32 s21, 0
	v_lshl_add_u64 v[40:41], v[38:39], 0, s[20:21]
	ds_read_b128 v[44:47], v36
	ds_read_b128 v[48:51], v36 offset:64
	ds_read_b128 v[52:55], v36 offset:128
	ds_read_b128 v[56:59], v36 offset:192
	s_mov_b32 s48, 0
	v_cmp_eq_u32_e32 vcc, 12, v175
.Llru_cf_mi:
	ds_read_u16 v68, v37
	ds_read_u16 v69, v37 offset:272
	ds_read_u16 v70, v37 offset:544
	ds_read_u16 v71, v37 offset:816
	s_waitcnt lgkmcnt(4)
	v_mfma_f32_16x16x32_bf16 v[60:63], v[44:47], v[4:7], 0
	v_mfma_f32_16x16x32_bf16 v[64:67], v[44:47], v[12:15], 0
	v_mfma_f32_16x16x32_bf16 v[60:63], v[48:51], v[8:11], v[60:63]
	v_mfma_f32_16x16x32_bf16 v[64:67], v[48:51], v[16:19], v[64:67]
	v_mfma_f32_16x16x32_bf16 v[60:63], v[52:55], v[20:23], v[60:63]
	v_mfma_f32_16x16x32_bf16 v[64:67], v[52:55], v[28:31], v[64:67]
	v_mfma_f32_16x16x32_bf16 v[60:63], v[56:59], v[24:27], v[60:63]
	v_mfma_f32_16x16x32_bf16 v[64:67], v[56:59], v[32:35], v[64:67]
	v_add_u32_e32 v36, s12, v36
	v_add_u32_e32 v37, s12, v37
	ds_read_b128 v[44:47], v36
	ds_read_b128 v[48:51], v36 offset:64
	ds_read_b128 v[52:55], v36 offset:128
	ds_read_b128 v[56:59], v36 offset:192
	s_nop 1
	v_fmamk_f32 v72, v60, 0xbfb8aa3b, v2
	v_fmamk_f32 v73, v61, 0xbfb8aa3b, v2
	v_fmamk_f32 v74, v62, 0xbfb8aa3b, v2
	v_fmamk_f32 v75, v63, 0xbfb8aa3b, v2
	v_fmamk_f32 v76, v64, 0xbfb8aa3b, v124
	v_fmamk_f32 v77, v65, 0xbfb8aa3b, v124
	v_fmamk_f32 v78, v66, 0xbfb8aa3b, v124
	v_fmamk_f32 v79, v67, 0xbfb8aa3b, v124
	v_exp_f32_e32 v72, v72
	v_exp_f32_e32 v73, v73
	v_exp_f32_e32 v74, v74
	v_exp_f32_e32 v75, v75
	v_exp_f32_e32 v76, v76
	v_exp_f32_e32 v77, v77
	v_exp_f32_e32 v78, v78
	v_exp_f32_e32 v79, v79
	v_add_f32_e32 v72, 1.0, v72
	v_add_f32_e32 v73, 1.0, v73
	v_add_f32_e32 v74, 1.0, v74
	v_add_f32_e32 v75, 1.0, v75
	v_add_f32_e32 v76, 1.0, v76
	v_add_f32_e32 v77, 1.0, v77
	v_add_f32_e32 v78, 1.0, v78
	v_add_f32_e32 v79, 1.0, v79
	v_rcp_f32_e32 v72, v72
	v_rcp_f32_e32 v73, v73
	v_rcp_f32_e32 v74, v74
	v_rcp_f32_e32 v75, v75
	v_rcp_f32_e32 v76, v76
	v_rcp_f32_e32 v77, v77
	v_rcp_f32_e32 v78, v78
	v_rcp_f32_e32 v79, v79
	v_mul_f32_e32 v72, v114, v72
	v_mul_f32_e32 v73, v114, v73
	v_mul_f32_e32 v74, v114, v74
	v_mul_f32_e32 v75, v114, v75
	s_waitcnt lgkmcnt(4)
	v_lshlrev_b32_e32 v68, 16, v68
	v_lshlrev_b32_e32 v69, 16, v69
	v_lshlrev_b32_e32 v70, 16, v70
	v_lshlrev_b32_e32 v71, 16, v71
	v_exp_f32_e32 v72, v72
	v_exp_f32_e32 v73, v73
	v_exp_f32_e32 v74, v74
	v_exp_f32_e32 v75, v75
	v_mul_f32_e32 v80, v76, v68
	v_mul_f32_e32 v81, v77, v69
	v_mul_f32_e32 v82, v78, v70
	v_mul_f32_e32 v83, v79, v71
	v_fma_f32 v84, -v72, v72, 1.0
	v_fma_f32 v85, -v73, v73, 1.0
	v_fma_f32 v86, -v74, v74, 1.0
	v_fma_f32 v87, -v75, v75, 1.0
	v_max_f32_e32 v84, 0, v84
	v_max_f32_e32 v85, 0, v85
	v_max_f32_e32 v86, 0, v86
	v_max_f32_e32 v87, 0, v87
	v_sqrt_f32_e32 v84, v84
	v_sqrt_f32_e32 v85, v85
	v_sqrt_f32_e32 v86, v86
	v_sqrt_f32_e32 v87, v87
	s_nop 0
	v_mul_f32_e32 v80, v84, v80
	v_mul_f32_e32 v81, v85, v81
	v_mul_f32_e32 v82, v86, v82
	v_mul_f32_e32 v83, v87, v83
	v_mul_f32_e32 v88, v73, v72
	v_fma_f32 v91, v73, v80, v81
	v_mul_f32_e32 v89, v74, v88
	v_fma_f32 v92, v74, v91, v82
	v_mul_f32_e32 v90, v75, v89
	v_fma_f32 v93, v75, v92, v83
	v_mov_b32_e32 v94, v90
	v_mov_b32_e32 v95, v90
	v_mov_b32_e32 v98, v93
	v_mov_b32_e32 v99, v93
	s_nop 0
	v_permlane16_swap_b32_e32 v94, v95
	v_permlane16_swap_b32_e32 v98, v99
	v_mov_b32_e32 v96, v94
	v_mov_b32_e32 v97, v95
	v_mov_b32_e32 v100, v98
	v_mov_b32_e32 v101, v99
	s_nop 1
	v_permlane32_swap_b32_e32 v94, v96
	v_permlane32_swap_b32_e32 v95, v97
	v_permlane32_swap_b32_e32 v98, v100
	v_permlane32_swap_b32_e32 v99, v101
	v_mul_f32_e32 v102, v95, v94
	v_fma_f32 v103, v95, v98, v99
	v_cndmask_b32_e64 v108, 1.0, v94, s[44:45]
	v_cndmask_b32_e64 v109, 0, v98, s[44:45]
	v_mul_f32_e32 v104, v96, v102
	v_fma_f32 v105, v96, v103, v100
	v_cndmask_b32_e64 v108, v108, v102, s[46:47]
	v_cndmask_b32_e64 v109, v109, v103, s[46:47]
	v_mul_f32_e32 v106, v97, v104
	v_fma_f32 v107, v97, v105, v101
	v_cndmask_b32_e32 v108, v108, v104, vcc
	v_cndmask_b32_e32 v109, v109, v105, vcc
	v_fma_f32 v110, v108, v125, v109
	v_fma_f32 v125, v106, v125, v107
	v_fma_f32 v126, v72, v110, v80
	v_fma_f32 v127, v88, v110, v91
	v_fma_f32 v128, v89, v110, v92
	v_fma_f32 v129, v90, v110, v93
	v_cvt_pk_bf16_f32 v130, v126, s0
	v_cvt_pk_bf16_f32 v131, v127, s0
	v_cvt_pk_bf16_f32 v132, v128, s0
	v_cvt_pk_bf16_f32 v133, v129, s0
	global_store_short v[38:39], v130, off offset:-4096
	global_store_short v[38:39], v131, off
	global_store_short v[40:41], v132, off offset:-4096
	global_store_short v[40:41], v133, off
	v_lshl_add_u64 v[38:39], v[38:39], 0, s[100:101]
	v_lshl_add_u64 v[40:41], v[40:41], 0, s[100:101]
	s_add_i32 s48, s48, 1
	s_cmp_lt_u32 s48, 8
	s_cbranch_scc1 .Llru_cf_mi
	s_add_i32 s49, s49, 1
	s_cmp_lt_u32 s49, 2
	s_cbranch_scc1 .Llru_cf_half
	s_waitcnt lgkmcnt(0)
	s_branch .LBB0_1283
.Llru_c_bwd:
	s_mov_b32 s49, 0
	s_mov_b32 s12, 0xffffef00
	s_mov_b32 s100, 0xffff0000
	s_mov_b32 s101, -1
.Llru_cb_half:
	s_xor_b32 s4, s49, s24
	s_lshl_b32 s4, s4, 7
	s_add_i32 s13, s4, s19
	v_add_u32_e32 v134, s13, v157
	v_mad_u32_u24 v36, v134, s30, v174
	v_add_u32_e32 v134, s13, v175
	v_mad_u32_u24 v37, v134, s30, v156
	s_add_i32 s20, s3, s13
	v_add_u32_e32 v134, s20, v175
	v_add_u32_e32 v134, 1, v134
	v_ashrrev_i32_e32 v135, 31, v134
	v_lshlrev_b64 v[134:135], 12, v[134:135]
	v_lshl_add_u64 v[38:39], v[118:119], 0, v[134:135]
	s_mov_b32 s20, 0x2000
	s_mov_b32 s21, 0
	v_lshl_add_u64 v[40:41], v[38:39], 0, s[20:21]
	ds_read_b128 v[44:47], v36
	ds_read_b128 v[48:51], v36 offset:64
	ds_read_b128 v[52:55], v36 offset:128
	ds_read_b128 v[56:59], v36 offset:192
	s_mov_b32 s48, 0
	v_cmp_eq_u32_e32 vcc, 0, v175
.Llru_cb_mi:
	ds_read_u16 v68, v37
	ds_read_u16 v69, v37 offset:272
	ds_read_u16 v70, v37 offset:544
	ds_read_u16 v71, v37 offset:816
	s_waitcnt lgkmcnt(4)
	v_mfma_f32_16x16x32_bf16 v[60:63], v[44:47], v[4:7], 0
	v_mfma_f32_16x16x32_bf16 v[64:67], v[44:47], v[12:15], 0
	v_mfma_f32_16x16x32_bf16 v[60:63], v[48:51], v[8:11], v[60:63]
	v_mfma_f32_16x16x32_bf16 v[64:67], v[48:51], v[16:19], v[64:67]
	v_mfma_f32_16x16x32_bf16 v[60:63], v[52:55], v[20:23], v[60:63]
	v_mfma_f32_16x16x32_bf16 v[64:67], v[52:55], v[28:31], v[64:67]
	v_mfma_f32_16x16x32_bf16 v[60:63], v[56:59], v[24:27], v[60:63]
	v_mfma_f32_16x16x32_bf16 v[64:67], v[56:59], v[32:35], v[64:67]
	v_add_u32_e32 v36, s12, v36
	v_add_u32_e32 v37, s12, v37
	ds_read_b128 v[44:47], v36
	ds_read_b128 v[48:51], v36 offset:64
	ds_read_b128 v[52:55], v36 offset:128
	ds_read_b128 v[56:59], v36 offset:192
	s_nop 1
	v_fmamk_f32 v72, v60, 0xbfb8aa3b, v2
	v_fmamk_f32 v73, v61, 0xbfb8aa3b, v2
	v_fmamk_f32 v74, v62, 0xbfb8aa3b, v2
	v_fmamk_f32 v75, v63, 0xbfb8aa3b, v2
	v_fmamk_f32 v76, v64, 0xbfb8aa3b, v124
	v_fmamk_f32 v77, v65, 0xbfb8aa3b, v124
	v_fmamk_f32 v78, v66, 0xbfb8aa3b, v124
	v_fmamk_f32 v79, v67, 0xbfb8aa3b, v124
	v_exp_f32_e32 v72, v72
	v_exp_f32_e32 v73, v73
	v_exp_f32_e32 v74, v74
	v_exp_f32_e32 v75, v75
	v_exp_f32_e32 v76, v76
	v_exp_f32_e32 v77, v77
	v_exp_f32_e32 v78, v78
	v_exp_f32_e32 v79, v79
	v_add_f32_e32 v72, 1.0, v72
	v_add_f32_e32 v73, 1.0, v73
	v_add_f32_e32 v74, 1.0, v74
	v_add_f32_e32 v75, 1.0, v75
	v_add_f32_e32 v76, 1.0, v76
	v_add_f32_e32 v77, 1.0, v77
	v_add_f32_e32 v78, 1.0, v78
	v_add_f32_e32 v79, 1.0, v79
	v_rcp_f32_e32 v72, v72
	v_rcp_f32_e32 v73, v73
	v_rcp_f32_e32 v74, v74
	v_rcp_f32_e32 v75, v75
	v_rcp_f32_e32 v76, v76
	v_rcp_f32_e32 v77, v77
	v_rcp_f32_e32 v78, v78
	v_rcp_f32_e32 v79, v79
	v_mul_f32_e32 v72, v114, v72
	v_mul_f32_e32 v73, v114, v73
	v_mul_f32_e32 v74, v114, v74
	v_mul_f32_e32 v75, v114, v75
	s_waitcnt lgkmcnt(4)
	v_lshlrev_b32_e32 v68, 16, v68
	v_lshlrev_b32_e32 v69, 16, v69
	v_lshlrev_b32_e32 v70, 16, v70
	v_lshlrev_b32_e32 v71, 16, v71
	v_exp_f32_e32 v72, v72
	v_exp_f32_e32 v73, v73
	v_exp_f32_e32 v74, v74
	v_exp_f32_e32 v75, v75
	v_mul_f32_e32 v80, v76, v68
	v_mul_f32_e32 v81, v77, v69
	v_mul_f32_e32 v82, v78, v70
	v_mul_f32_e32 v83, v79, v71
	v_fma_f32 v84, -v72, v72, 1.0
	v_fma_f32 v85, -v73, v73, 1.0
	v_fma_f32 v86, -v74, v74, 1.0
	v_fma_f32 v87, -v75, v75, 1.0
	v_max_f32_e32 v84, 0, v84
	v_max_f32_e32 v85, 0, v85
	v_max_f32_e32 v86, 0, v86
	v_max_f32_e32 v87, 0, v87
	v_sqrt_f32_e32 v84, v84
	v_sqrt_f32_e32 v85, v85
	v_sqrt_f32_e32 v86, v86
	v_sqrt_f32_e32 v87, v87
	s_nop 0
	v_mul_f32_e32 v80, v84, v80
	v_mul_f32_e32 v81, v85, v81
	v_mul_f32_e32 v82, v86, v82
	v_mul_f32_e32 v83, v87, v83
	v_mul_f32_e32 v88, v74, v75
	v_fma_f32 v91, v74, v83, v82
	v_mul_f32_e32 v89, v73, v88
	v_fma_f32 v92, v73, v91, v81
	v_mul_f32_e32 v90, v72, v89
	v_fma_f32 v93, v72, v92, v80
	v_mov_b32_e32 v94, v90
	v_mov_b32_e32 v95, v90
	v_mov_b32_e32 v98, v93
	v_mov_b32_e32 v99, v93
	s_nop 0
	v_permlane16_swap_b32_e32 v94, v95
	v_permlane16_swap_b32_e32 v98, v99
	v_mov_b32_e32 v96, v94
	v_mov_b32_e32 v97, v95
	v_mov_b32_e32 v100, v98
	v_mov_b32_e32 v101, v99
	s_nop 1
	v_permlane32_swap_b32_e32 v94, v96
	v_permlane32_swap_b32_e32 v95, v97
	v_permlane32_swap_b32_e32 v98, v100
	v_permlane32_swap_b32_e32 v99, v101
	v_mul_f32_e32 v102, v96, v97
	v_fma_f32 v103, v96, v101, v100
	v_cndmask_b32_e64 v108, 1.0, v97, s[44:45]
	v_cndmask_b32_e64 v109, 0, v101, s[44:45]
	v_mul_f32_e32 v104, v95, v102
	v_fma_f32 v105, v95, v103, v99
	v_cndmask_b32_e64 v108, v108, v102, s[46:47]
	v_cndmask_b32_e64 v109, v109, v103, s[46:47]
	v_mul_f32_e32 v106, v94, v104
	v_fma_f32 v107, v94, v105, v98
	v_cndmask_b32_e32 v108, v108, v104, vcc
	v_cndmask_b32_e32 v109, v109, v105, vcc
	v_fma_f32 v110, v108, v125, v109
	v_fma_f32 v125, v106, v125, v107
	v_fma_f32 v129, v75, v110, v83
	v_fma_f32 v128, v88, v110, v91
	v_fma_f32 v127, v89, v110, v92
	v_fma_f32 v126, v90, v110, v93
	v_cvt_pk_bf16_f32 v130, v126, s0
	v_cvt_pk_bf16_f32 v131, v127, s0
	v_cvt_pk_bf16_f32 v132, v128, s0
	v_cvt_pk_bf16_f32 v133, v129, s0
	global_store_short v[38:39], v130, off offset:-4096
	global_store_short v[38:39], v131, off
	global_store_short v[40:41], v132, off offset:-4096
	global_store_short v[40:41], v133, off
	v_lshl_add_u64 v[38:39], v[38:39], 0, s[100:101]
	v_lshl_add_u64 v[40:41], v[40:41], 0, s[100:101]
	s_add_i32 s48, s48, 1
	s_cmp_lt_u32 s48, 8
	s_cbranch_scc1 .Llru_cb_mi
	s_add_i32 s49, s49, 1
	s_cmp_lt_u32 s49, 2
	s_cbranch_scc1 .Llru_cb_half
	s_waitcnt lgkmcnt(0)
	s_branch .LBB0_1283

.Llru_lf_half:
	s_xor_b32 s4, s49, s24
	s_lshl_b32 s4, s4, 7
	s_add_i32 s13, s4, s61
	v_add_u32_e32 v192, s13, v157
	v_mad_u32_u24 v76, v192, s30, v174
	v_add_u32_e32 v192, s13, v175
	v_mad_u32_u24 v77, v192, s30, v156
	s_add_i32 s3, s2, s13
	v_add_u32_e32 v192, s3, v175
	v_add_u32_e32 v192, 1, v192
	v_ashrrev_i32_e32 v193, 31, v192
	v_lshlrev_b64 v[192:193], 12, v[192:193]
	v_lshl_add_u64 v[78:79], v[166:167], 0, v[192:193]
	s_mov_b32 s0, 0x2000
	s_mov_b32 s1, 0
	v_lshl_add_u64 v[80:81], v[78:79], 0, s[0:1]
	ds_read_b128 v[84:87], v76
	ds_read_b128 v[88:91], v76 offset:64
	ds_read_b128 v[92:95], v76 offset:128
	ds_read_b128 v[96:99], v76 offset:192
	s_mov_b32 s48, 0
	v_cmp_eq_u32_e32 vcc, 12, v175
.Llru_lf_mi:
	ds_read_u16 v108, v77
	ds_read_u16 v109, v77 offset:272
	ds_read_u16 v110, v77 offset:544
	ds_read_u16 v111, v77 offset:816
	s_waitcnt lgkmcnt(4)
	v_mfma_f32_16x16x32_bf16 v[100:103], v[84:87], v[4:7], 0
	v_mfma_f32_16x16x32_bf16 v[104:107], v[84:87], v[8:11], 0
	v_mfma_f32_16x16x32_bf16 v[100:103], v[88:91], v[12:15], v[100:103]
	v_mfma_f32_16x16x32_bf16 v[104:107], v[88:91], v[16:19], v[104:107]
	v_mfma_f32_16x16x32_bf16 v[100:103], v[92:95], v[20:23], v[100:103]
	v_mfma_f32_16x16x32_bf16 v[104:107], v[92:95], v[24:27], v[104:107]
	v_mfma_f32_16x16x32_bf16 v[100:103], v[96:99], v[28:31], v[100:103]
	v_mfma_f32_16x16x32_bf16 v[104:107], v[96:99], v[32:35], v[104:107]
	v_add_u32_e32 v76, s12, v76
	v_add_u32_e32 v77, s12, v77
	ds_read_b128 v[84:87], v76
	ds_read_b128 v[88:91], v76 offset:64
	ds_read_b128 v[92:95], v76 offset:128
	ds_read_b128 v[96:99], v76 offset:192
	s_nop 1
	v_fmamk_f32 v112, v100, 0xbfb8aa3b, v2
	v_fmamk_f32 v113, v101, 0xbfb8aa3b, v2
	v_fmamk_f32 v114, v102, 0xbfb8aa3b, v2
	v_fmamk_f32 v115, v103, 0xbfb8aa3b, v2
	v_fmamk_f32 v116, v104, 0xbfb8aa3b, v197
	v_fmamk_f32 v117, v105, 0xbfb8aa3b, v197
	v_fmamk_f32 v118, v106, 0xbfb8aa3b, v197
	v_fmamk_f32 v119, v107, 0xbfb8aa3b, v197
	v_exp_f32_e32 v112, v112
	v_exp_f32_e32 v113, v113
	v_exp_f32_e32 v114, v114
	v_exp_f32_e32 v115, v115
	v_exp_f32_e32 v116, v116
	v_exp_f32_e32 v117, v117
	v_exp_f32_e32 v118, v118
	v_exp_f32_e32 v119, v119
	v_add_f32_e32 v112, 1.0, v112
	v_add_f32_e32 v113, 1.0, v113
	v_add_f32_e32 v114, 1.0, v114
	v_add_f32_e32 v115, 1.0, v115
	v_add_f32_e32 v116, 1.0, v116
	v_add_f32_e32 v117, 1.0, v117
	v_add_f32_e32 v118, 1.0, v118
	v_add_f32_e32 v119, 1.0, v119
	v_rcp_f32_e32 v112, v112
	v_rcp_f32_e32 v113, v113
	v_rcp_f32_e32 v114, v114
	v_rcp_f32_e32 v115, v115
	v_rcp_f32_e32 v116, v116
	v_rcp_f32_e32 v117, v117
	v_rcp_f32_e32 v118, v118
	v_rcp_f32_e32 v119, v119
	v_mul_f32_e32 v112, v160, v112
	v_mul_f32_e32 v113, v160, v113
	v_mul_f32_e32 v114, v160, v114
	v_mul_f32_e32 v115, v160, v115
	s_waitcnt lgkmcnt(4)
	v_lshlrev_b32_e32 v108, 16, v108
	v_lshlrev_b32_e32 v109, 16, v109
	v_lshlrev_b32_e32 v110, 16, v110
	v_lshlrev_b32_e32 v111, 16, v111
	v_exp_f32_e32 v112, v112
	v_exp_f32_e32 v113, v113
	v_exp_f32_e32 v114, v114
	v_exp_f32_e32 v115, v115
	v_mul_f32_e32 v120, v116, v108
	v_mul_f32_e32 v121, v117, v109
	v_mul_f32_e32 v122, v118, v110
	v_mul_f32_e32 v123, v119, v111
	v_fma_f32 v124, -v112, v112, 1.0
	v_fma_f32 v125, -v113, v113, 1.0
	v_fma_f32 v126, -v114, v114, 1.0
	v_fma_f32 v127, -v115, v115, 1.0
	v_max_f32_e32 v124, 0, v124
	v_max_f32_e32 v125, 0, v125
	v_max_f32_e32 v126, 0, v126
	v_max_f32_e32 v127, 0, v127
	v_sqrt_f32_e32 v124, v124
	v_sqrt_f32_e32 v125, v125
	v_sqrt_f32_e32 v126, v126
	v_sqrt_f32_e32 v127, v127
	s_nop 0
	v_mul_f32_e32 v120, v124, v120
	v_mul_f32_e32 v121, v125, v121
	v_mul_f32_e32 v122, v126, v122
	v_mul_f32_e32 v123, v127, v123
	v_mul_f32_e32 v128, v113, v112
	v_fma_f32 v131, v113, v120, v121
	v_mul_f32_e32 v129, v114, v128
	v_fma_f32 v132, v114, v131, v122
	v_mul_f32_e32 v130, v115, v129
	v_fma_f32 v133, v115, v132, v123
	v_mov_b32_e32 v134, v130
	v_mov_b32_e32 v135, v130
	v_mov_b32_e32 v138, v133
	v_mov_b32_e32 v139, v133
	s_nop 0
	v_permlane16_swap_b32_e32 v134, v135
	v_permlane16_swap_b32_e32 v138, v139
	v_mov_b32_e32 v136, v134
	v_mov_b32_e32 v137, v135
	v_mov_b32_e32 v140, v138
	v_mov_b32_e32 v141, v139
	s_nop 1
	v_permlane32_swap_b32_e32 v134, v136
	v_permlane32_swap_b32_e32 v135, v137
	v_permlane32_swap_b32_e32 v138, v140
	v_permlane32_swap_b32_e32 v139, v141
	v_mul_f32_e32 v142, v135, v134
	v_fma_f32 v143, v135, v138, v139
	v_cndmask_b32_e64 v148, 1.0, v134, s[44:45]
	v_cndmask_b32_e64 v149, 0, v138, s[44:45]
	v_mul_f32_e32 v144, v136, v142
	v_fma_f32 v145, v136, v143, v140
	v_cndmask_b32_e64 v148, v148, v142, s[46:47]
	v_cndmask_b32_e64 v149, v149, v143, s[46:47]
	v_mul_f32_e32 v146, v137, v144
	v_fma_f32 v147, v137, v145, v141
	v_cndmask_b32_e32 v148, v148, v144, vcc
	v_cndmask_b32_e32 v149, v149, v145, vcc
	v_fma_f32 v150, v148, v198, v149
	v_fma_f32 v198, v146, v198, v147
	v_fma_f32 v184, v112, v150, v120
	v_fma_f32 v185, v128, v150, v131
	v_fma_f32 v186, v129, v150, v132
	v_fma_f32 v187, v130, v150, v133
	v_cvt_pk_bf16_f32 v188, v184, s0
	v_cvt_pk_bf16_f32 v189, v185, s0
	v_cvt_pk_bf16_f32 v190, v186, s0
	v_cvt_pk_bf16_f32 v191, v187, s0
	global_store_short v[78:79], v188, off offset:-4096
	global_store_short v[78:79], v189, off
	global_store_short v[80:81], v190, off offset:-4096
	global_store_short v[80:81], v191, off
	v_lshl_add_u64 v[78:79], v[78:79], 0, s[100:101]
	v_lshl_add_u64 v[80:81], v[80:81], 0, s[100:101]
	s_add_i32 s48, s48, 1
	s_cmp_lt_u32 s48, 8
	s_cbranch_scc1 .Llru_lf_mi
	s_add_i32 s49, s49, 1
	s_cmp_lt_u32 s49, 2
	s_cbranch_scc1 .Llru_lf_half
	s_waitcnt lgkmcnt(0)
	s_branch .LBB0_1292

.Llru_lb_half:
	s_xor_b32 s4, s49, s24
	s_lshl_b32 s4, s4, 7
	s_add_i32 s13, s4, s61
	v_add_u32_e32 v192, s13, v157
	v_mad_u32_u24 v76, v192, s30, v174
	v_add_u32_e32 v192, s13, v175
	v_mad_u32_u24 v77, v192, s30, v156
	s_add_i32 s3, s2, s13
	v_add_u32_e32 v192, s3, v175
	v_add_u32_e32 v192, 1, v192
	v_ashrrev_i32_e32 v193, 31, v192
	v_lshlrev_b64 v[192:193], 12, v[192:193]
	v_lshl_add_u64 v[78:79], v[166:167], 0, v[192:193]
	s_mov_b32 s0, 0x2000
	s_mov_b32 s1, 0
	v_lshl_add_u64 v[80:81], v[78:79], 0, s[0:1]
	ds_read_b128 v[84:87], v76
	ds_read_b128 v[88:91], v76 offset:64
	ds_read_b128 v[92:95], v76 offset:128
	ds_read_b128 v[96:99], v76 offset:192
	s_mov_b32 s48, 0
	v_cmp_eq_u32_e32 vcc, 0, v175
.Llru_lb_mi:
	ds_read_u16 v108, v77
	ds_read_u16 v109, v77 offset:272
	ds_read_u16 v110, v77 offset:544
	ds_read_u16 v111, v77 offset:816
	s_waitcnt lgkmcnt(4)
	v_mfma_f32_16x16x32_bf16 v[100:103], v[84:87], v[4:7], 0
	v_mfma_f32_16x16x32_bf16 v[104:107], v[84:87], v[8:11], 0
	v_mfma_f32_16x16x32_bf16 v[100:103], v[88:91], v[12:15], v[100:103]
	v_mfma_f32_16x16x32_bf16 v[104:107], v[88:91], v[16:19], v[104:107]
	v_mfma_f32_16x16x32_bf16 v[100:103], v[92:95], v[20:23], v[100:103]
	v_mfma_f32_16x16x32_bf16 v[104:107], v[92:95], v[24:27], v[104:107]
	v_mfma_f32_16x16x32_bf16 v[100:103], v[96:99], v[28:31], v[100:103]
	v_mfma_f32_16x16x32_bf16 v[104:107], v[96:99], v[32:35], v[104:107]
	v_add_u32_e32 v76, s12, v76
	v_add_u32_e32 v77, s12, v77
	ds_read_b128 v[84:87], v76
	ds_read_b128 v[88:91], v76 offset:64
	ds_read_b128 v[92:95], v76 offset:128
	ds_read_b128 v[96:99], v76 offset:192
	s_nop 1
	v_fmamk_f32 v112, v100, 0xbfb8aa3b, v2
	v_fmamk_f32 v113, v101, 0xbfb8aa3b, v2
	v_fmamk_f32 v114, v102, 0xbfb8aa3b, v2
	v_fmamk_f32 v115, v103, 0xbfb8aa3b, v2
	v_fmamk_f32 v116, v104, 0xbfb8aa3b, v197
	v_fmamk_f32 v117, v105, 0xbfb8aa3b, v197
	v_fmamk_f32 v118, v106, 0xbfb8aa3b, v197
	v_fmamk_f32 v119, v107, 0xbfb8aa3b, v197
	v_exp_f32_e32 v112, v112
	v_exp_f32_e32 v113, v113
	v_exp_f32_e32 v114, v114
	v_exp_f32_e32 v115, v115
	v_exp_f32_e32 v116, v116
	v_exp_f32_e32 v117, v117
	v_exp_f32_e32 v118, v118
	v_exp_f32_e32 v119, v119
	v_add_f32_e32 v112, 1.0, v112
	v_add_f32_e32 v113, 1.0, v113
	v_add_f32_e32 v114, 1.0, v114
	v_add_f32_e32 v115, 1.0, v115
	v_add_f32_e32 v116, 1.0, v116
	v_add_f32_e32 v117, 1.0, v117
	v_add_f32_e32 v118, 1.0, v118
	v_add_f32_e32 v119, 1.0, v119
	v_rcp_f32_e32 v112, v112
	v_rcp_f32_e32 v113, v113
	v_rcp_f32_e32 v114, v114
	v_rcp_f32_e32 v115, v115
	v_rcp_f32_e32 v116, v116
	v_rcp_f32_e32 v117, v117
	v_rcp_f32_e32 v118, v118
	v_rcp_f32_e32 v119, v119
	v_mul_f32_e32 v112, v160, v112
	v_mul_f32_e32 v113, v160, v113
	v_mul_f32_e32 v114, v160, v114
	v_mul_f32_e32 v115, v160, v115
	s_waitcnt lgkmcnt(4)
	v_lshlrev_b32_e32 v108, 16, v108
	v_lshlrev_b32_e32 v109, 16, v109
	v_lshlrev_b32_e32 v110, 16, v110
	v_lshlrev_b32_e32 v111, 16, v111
	v_exp_f32_e32 v112, v112
	v_exp_f32_e32 v113, v113
	v_exp_f32_e32 v114, v114
	v_exp_f32_e32 v115, v115
	v_mul_f32_e32 v120, v116, v108
	v_mul_f32_e32 v121, v117, v109
	v_mul_f32_e32 v122, v118, v110
	v_mul_f32_e32 v123, v119, v111
	v_fma_f32 v124, -v112, v112, 1.0
	v_fma_f32 v125, -v113, v113, 1.0
	v_fma_f32 v126, -v114, v114, 1.0
	v_fma_f32 v127, -v115, v115, 1.0
	v_max_f32_e32 v124, 0, v124
	v_max_f32_e32 v125, 0, v125
	v_max_f32_e32 v126, 0, v126
	v_max_f32_e32 v127, 0, v127
	v_sqrt_f32_e32 v124, v124
	v_sqrt_f32_e32 v125, v125
	v_sqrt_f32_e32 v126, v126
	v_sqrt_f32_e32 v127, v127
	s_nop 0
	v_mul_f32_e32 v120, v124, v120
	v_mul_f32_e32 v121, v125, v121
	v_mul_f32_e32 v122, v126, v122
	v_mul_f32_e32 v123, v127, v123
	v_mul_f32_e32 v128, v114, v115
	v_fma_f32 v131, v114, v123, v122
	v_mul_f32_e32 v129, v113, v128
	v_fma_f32 v132, v113, v131, v121
	v_mul_f32_e32 v130, v112, v129
	v_fma_f32 v133, v112, v132, v120
	v_mov_b32_e32 v134, v130
	v_mov_b32_e32 v135, v130
	v_mov_b32_e32 v138, v133
	v_mov_b32_e32 v139, v133
	s_nop 0
	v_permlane16_swap_b32_e32 v134, v135
	v_permlane16_swap_b32_e32 v138, v139
	v_mov_b32_e32 v136, v134
	v_mov_b32_e32 v137, v135
	v_mov_b32_e32 v140, v138
	v_mov_b32_e32 v141, v139
	s_nop 1
	v_permlane32_swap_b32_e32 v134, v136
	v_permlane32_swap_b32_e32 v135, v137
	v_permlane32_swap_b32_e32 v138, v140
	v_permlane32_swap_b32_e32 v139, v141
	v_mul_f32_e32 v142, v136, v137
	v_fma_f32 v143, v136, v141, v140
	v_cndmask_b32_e64 v148, 1.0, v137, s[44:45]
	v_cndmask_b32_e64 v149, 0, v141, s[44:45]
	v_mul_f32_e32 v144, v135, v142
	v_fma_f32 v145, v135, v143, v139
	v_cndmask_b32_e64 v148, v148, v142, s[46:47]
	v_cndmask_b32_e64 v149, v149, v143, s[46:47]
	v_mul_f32_e32 v146, v134, v144
	v_fma_f32 v147, v134, v145, v138
	v_cndmask_b32_e32 v148, v148, v144, vcc
	v_cndmask_b32_e32 v149, v149, v145, vcc
	v_fma_f32 v150, v148, v198, v149
	v_fma_f32 v198, v146, v198, v147
	v_fma_f32 v187, v115, v150, v123
	v_fma_f32 v186, v128, v150, v131
	v_fma_f32 v185, v129, v150, v132
	v_fma_f32 v184, v130, v150, v133
	v_cvt_pk_bf16_f32 v188, v184, s0
	v_cvt_pk_bf16_f32 v189, v185, s0
	v_cvt_pk_bf16_f32 v190, v186, s0
	v_cvt_pk_bf16_f32 v191, v187, s0
	global_store_short v[78:79], v188, off offset:-4096
	global_store_short v[78:79], v189, off
	global_store_short v[80:81], v190, off offset:-4096
	global_store_short v[80:81], v191, off
	v_lshl_add_u64 v[78:79], v[78:79], 0, s[100:101]
	v_lshl_add_u64 v[80:81], v[80:81], 0, s[100:101]
	s_add_i32 s48, s48, 1
	s_cmp_lt_u32 s48, 8
	s_cbranch_scc1 .Llru_lb_mi
	s_add_i32 s49, s49, 1
	s_cmp_lt_u32 s49, 2
	s_cbranch_scc1 .Llru_lb_half
	s_waitcnt lgkmcnt(0)
	s_branch .LBB0_1292
